# norm: bf16 H rows stored as 16-byte write-through stores (neighbour lanes exchange an 8-byte piece by DPP)
# baseline (speedup 1.0000x reference)
.LBB0_1043:
	s_or_b64 exec, exec, s[52:53]
	s_mov_b64 s[52:53], -1
	s_and_b64 vcc, exec, s[42:43]
	v_pk_mul_f32 v[120:121], v[94:95], v[178:179] op_sel_hi:[1,0]
	v_pk_mul_f32 v[118:119], v[90:91], v[178:179] op_sel_hi:[1,0]
	v_pk_mul_f32 v[116:117], v[86:87], v[178:179] op_sel_hi:[1,0]
	v_pk_mul_f32 v[114:115], v[82:83], v[178:179] op_sel_hi:[1,0]
	s_cbranch_vccnz .LBB0_1046
	v_lshl_add_u64 v[122:123], s[80:81], 0, v[162:163]
	global_store_dwordx4 v[122:123], v[94:97], off sc1
	global_store_dwordx4 v[122:123], v[90:93], off offset:1024 sc1
	global_store_dwordx4 v[122:123], v[86:89], off offset:2048 sc1
	global_store_dwordx4 v[122:123], v[82:85], off offset:3072 sc1
	v_pk_add_f32 v[90:91], v[110:111], 1.0 op_sel_hi:[1,0]
	v_pk_add_f32 v[86:87], v[112:113], 1.0 op_sel_hi:[1,0]
	v_pk_mul_f32 v[82:83], v[96:97], v[178:179] op_sel_hi:[1,0]
	s_mov_b32 s12, 0x1800000
	v_pk_fma_f32 v[82:83], v[86:87], v[82:83], v[28:29]
	v_pk_fma_f32 v[86:87], v[90:91], v[120:121], v[26:27]
	v_pk_add_f32 v[90:91], v[108:109], 1.0 op_sel_hi:[1,0]
	v_cvt_pk_bf16_f32 v86, v86, v87
	v_cvt_pk_bf16_f32 v87, v82, v83
	v_add_co_u32_e32 v82, vcc, s12, v200
	v_pk_add_f32 v[94:95], v[106:107], 1.0 op_sel_hi:[1,0]
	s_nop 0
	v_addc_co_u32_e32 v83, vcc, 0, v201, vcc
	v_mov_b32_e32 v236, v86
	v_mov_b32_e32 v237, v87
	v_pk_mul_f32 v[86:87], v[92:93], v[178:179] op_sel_hi:[1,0]
	s_nop 0
	v_pk_fma_f32 v[86:87], v[90:91], v[86:87], v[36:37]
	v_pk_fma_f32 v[90:91], v[94:95], v[118:119], v[34:35]
	v_pk_add_f32 v[94:95], v[102:103], 1.0 op_sel_hi:[1,0]
	v_cvt_pk_bf16_f32 v90, v90, v91
	v_cvt_pk_bf16_f32 v91, v86, v87
	v_mov_b32_e32 v238, v90
	v_mov_b32_e32 v239, v91
	v_pk_mul_f32 v[86:87], v[88:89], v[178:179] op_sel_hi:[1,0]
	v_pk_add_f32 v[90:91], v[104:105], 1.0 op_sel_hi:[1,0]
	s_nop 0
	v_pk_fma_f32 v[86:87], v[90:91], v[86:87], v[44:45]
	v_pk_fma_f32 v[90:91], v[94:95], v[116:117], v[42:43]
	v_pk_add_f32 v[94:95], v[98:99], 1.0 op_sel_hi:[1,0]
	v_cvt_pk_bf16_f32 v90, v90, v91
	v_cvt_pk_bf16_f32 v91, v86, v87
	v_mov_b32_e32 v240, v90
	v_mov_b32_e32 v241, v91
	v_pk_mul_f32 v[86:87], v[84:85], v[178:179] op_sel_hi:[1,0]
	v_pk_add_f32 v[90:91], v[100:101], 1.0 op_sel_hi:[1,0]
	s_nop 0
	v_pk_fma_f32 v[86:87], v[90:91], v[86:87], v[48:49]
	v_pk_fma_f32 v[90:91], v[94:95], v[114:115], v[46:47]
	s_nop 0
	v_cvt_pk_bf16_f32 v90, v90, v91
	v_cvt_pk_bf16_f32 v91, v86, v87
	v_mov_b32_e32 v242, v90
	v_mov_b32_e32 v243, v91
	s_mov_b32 s96, 0xaaaaaaaa
	s_mov_b32 s97, s96
	v_and_b32_e32 v232, 1, v210
	v_mov_b32_e32 v233, 0
	v_mul_u32_u24_e32 v232, 0x1f8, v232
	s_nop 0
	v_lshl_add_u64 v[234:235], v[82:83], 0, v[232:233]
	v_cndmask_b32_e64 v244, v238, v236, s[96:97]
	v_cndmask_b32_e64 v245, v239, v237, s[96:97]
	s_nop 1
	v_mov_b32_dpp v246, v244 quad_perm:[1,0,3,2] row_mask:0xf bank_mask:0xf
	v_mov_b32_dpp v247, v245 quad_perm:[1,0,3,2] row_mask:0xf bank_mask:0xf
	s_nop 1
	v_cndmask_b32_e64 v248, v236, v246, s[96:97]
	v_cndmask_b32_e64 v249, v237, v247, s[96:97]
	v_cndmask_b32_e64 v250, v246, v238, s[96:97]
	v_cndmask_b32_e64 v251, v247, v239, s[96:97]
	s_nop 0
	global_store_dwordx4 v[234:235], v[248:251], off sc1
	s_nop 1
	v_cndmask_b32_e64 v244, v242, v240, s[96:97]
	v_cndmask_b32_e64 v245, v243, v241, s[96:97]
	s_nop 1
	v_mov_b32_dpp v246, v244 quad_perm:[1,0,3,2] row_mask:0xf bank_mask:0xf
	v_mov_b32_dpp v247, v245 quad_perm:[1,0,3,2] row_mask:0xf bank_mask:0xf
	s_nop 1
	v_cndmask_b32_e64 v248, v240, v246, s[96:97]
	v_cndmask_b32_e64 v249, v241, v247, s[96:97]
	v_cndmask_b32_e64 v250, v246, v242, s[96:97]
	v_cndmask_b32_e64 v251, v247, v243, s[96:97]
	s_nop 0
	global_store_dwordx4 v[234:235], v[248:251], off offset:1024 sc1
	s_nop 1
	s_cbranch_execz .LBB0_1047

.LBB0_1050:
	s_mov_b64 s[40:41], -1
	s_and_b64 vcc, exec, s[42:43]
	v_pk_mul_f32 v[88:89], v[50:51], v[178:179] op_sel:[0,1]
	v_pk_mul_f32 v[86:87], v[54:55], v[178:179] op_sel:[0,1]
	v_pk_mul_f32 v[84:85], v[58:59], v[178:179] op_sel:[0,1]
	v_pk_mul_f32 v[82:83], v[62:63], v[178:179] op_sel:[0,1]
	s_cbranch_vccnz .LBB0_1052
	v_ashrrev_i32_e32 v197, 31, v196
	v_lshlrev_b64 v[90:91], 12, v[196:197]
	v_lshl_add_u64 v[90:91], v[148:149], 0, v[90:91]
	v_pk_mul_f32 v[92:93], v[52:53], v[178:179] op_sel:[0,1]
	v_pk_add_f32 v[94:95], v[68:69], 1.0 op_sel_hi:[1,0]
	v_pk_add_f32 v[96:97], v[66:67], 1.0 op_sel_hi:[1,0]
	global_store_dwordx4 v[90:91], v[50:53], off sc1
	global_store_dwordx4 v[90:91], v[54:57], off offset:1024 sc1
	global_store_dwordx4 v[90:91], v[58:61], off offset:2048 sc1
	global_store_dwordx4 v[90:91], v[62:65], off offset:3072 sc1
	v_lshlrev_b64 v[90:91], 11, v[196:197]
	v_pk_fma_f32 v[92:93], v[94:95], v[92:93], v[24:25]
	v_pk_fma_f32 v[94:95], v[96:97], v[88:89], v[22:23]
	v_lshl_add_u64 v[90:91], v[150:151], 0, v[90:91]
	v_cvt_pk_bf16_f32 v94, v94, v95
	v_cvt_pk_bf16_f32 v95, v92, v93
	v_mov_b32_e32 v236, v94
	v_mov_b32_e32 v237, v95
	v_pk_mul_f32 v[92:93], v[56:57], v[178:179] op_sel:[0,1]
	v_pk_add_f32 v[94:95], v[72:73], 1.0 op_sel_hi:[1,0]
	v_pk_add_f32 v[96:97], v[70:71], 1.0 op_sel_hi:[1,0]
	v_pk_fma_f32 v[92:93], v[94:95], v[92:93], v[20:21]
	v_pk_fma_f32 v[94:95], v[96:97], v[86:87], v[18:19]
	v_pk_add_f32 v[96:97], v[74:75], 1.0 op_sel_hi:[1,0]
	v_cvt_pk_bf16_f32 v94, v94, v95
	v_cvt_pk_bf16_f32 v95, v92, v93
	v_mov_b32_e32 v238, v94
	v_mov_b32_e32 v239, v95
	v_pk_mul_f32 v[92:93], v[60:61], v[178:179] op_sel:[0,1]
	v_pk_add_f32 v[94:95], v[76:77], 1.0 op_sel_hi:[1,0]
	s_mov_b64 s[40:41], 0
	v_pk_fma_f32 v[92:93], v[94:95], v[92:93], v[8:9]
	v_pk_fma_f32 v[94:95], v[96:97], v[84:85], v[6:7]
	v_pk_add_f32 v[96:97], v[78:79], 1.0 op_sel_hi:[1,0]
	v_cvt_pk_bf16_f32 v94, v94, v95
	v_cvt_pk_bf16_f32 v95, v92, v93
	v_mov_b32_e32 v240, v94
	v_mov_b32_e32 v241, v95
	v_pk_mul_f32 v[92:93], v[64:65], v[178:179] op_sel:[0,1]
	v_pk_add_f32 v[94:95], v[80:81], 1.0 op_sel_hi:[1,0]
	s_nop 0
	v_pk_fma_f32 v[92:93], v[94:95], v[92:93], v[4:5]
	v_pk_fma_f32 v[94:95], v[96:97], v[82:83], v[2:3]
	s_nop 0
	v_cvt_pk_bf16_f32 v94, v94, v95
	v_cvt_pk_bf16_f32 v95, v92, v93
	v_mov_b32_e32 v242, v94
	v_mov_b32_e32 v243, v95
	s_mov_b32 s96, 0xaaaaaaaa
	s_mov_b32 s97, s96
	v_and_b32_e32 v232, 1, v210
	v_mov_b32_e32 v233, 0
	v_mul_u32_u24_e32 v232, 0x1f8, v232
	s_nop 0
	v_lshl_add_u64 v[234:235], v[90:91], 0, v[232:233]
	v_cndmask_b32_e64 v244, v238, v236, s[96:97]
	v_cndmask_b32_e64 v245, v239, v237, s[96:97]
	s_nop 1
	v_mov_b32_dpp v246, v244 quad_perm:[1,0,3,2] row_mask:0xf bank_mask:0xf
	v_mov_b32_dpp v247, v245 quad_perm:[1,0,3,2] row_mask:0xf bank_mask:0xf
	s_nop 1
	v_cndmask_b32_e64 v248, v236, v246, s[96:97]
	v_cndmask_b32_e64 v249, v237, v247, s[96:97]
	v_cndmask_b32_e64 v250, v246, v238, s[96:97]
	v_cndmask_b32_e64 v251, v247, v239, s[96:97]
	s_nop 0
	global_store_dwordx4 v[234:235], v[248:251], off sc1
	s_nop 1
	v_cndmask_b32_e64 v244, v242, v240, s[96:97]
	v_cndmask_b32_e64 v245, v243, v241, s[96:97]
	s_nop 1
	v_mov_b32_dpp v246, v244 quad_perm:[1,0,3,2] row_mask:0xf bank_mask:0xf
	v_mov_b32_dpp v247, v245 quad_perm:[1,0,3,2] row_mask:0xf bank_mask:0xf
	s_nop 1
	v_cndmask_b32_e64 v248, v240, v246, s[96:97]
	v_cndmask_b32_e64 v249, v241, v247, s[96:97]
	v_cndmask_b32_e64 v250, v246, v242, s[96:97]
	v_cndmask_b32_e64 v251, v247, v243, s[96:97]
	s_nop 0
	global_store_dwordx4 v[234:235], v[248:251], off offset:1024 sc1
	s_nop 1
